# v072 with the prefetched tile's LDS write moved two MFMA groups later in the QK group (more slack for the prefetch loads to land)
# baseline (speedup 1.0000x reference)
.Lattn_fx_top:
	s_add_i32 s11, s10, -1
	s_min_i32 s1, s11, s58
	s_mul_i32 s44, s1, 0xa0000
	s_add_u32 s44, s3, s44
	s_addc_u32 s45, s12, 0
	s_lshl_b32 s46, s1, 7
	s_add_u32 s46, s15, s46
	s_addc_u32 s47, s23, 0
	s_add_i32 s24, s10, -2
	s_cmp_lt_u32 s24, s16
	s_cselect_b64 s[0:1], -1, 0
	global_load_dwordx4 v[154:157], v252, s[44:45] offset:1024
	global_load_dwordx4 v[158:161], v253, s[46:47]
	v_exp_f32_e32 v66, v66
	v_exp_f32_e32 v67, v67
	v_exp_f32_e32 v68, v68
	v_exp_f32_e32 v69, v69
	v_add_f32_e32 v246, v66, v67
	v_cvt_pk_bf16_f32 v66, v66, v67
	s_waitcnt lgkmcnt(0)
	v_mfma_f32_32x32x16_bf16 v[114:129], v[162:165], v[130:133], v[50:65]
	ds_read_b128 v[86:89], v248 offset:36864
	ds_read_b128 v[216:219], v248 offset:41472
	v_exp_f32_e32 v70, v70
	v_exp_f32_e32 v71, v71
	v_add_f32_e32 v246, v68, v246
	v_add_f32_e32 v246, v69, v246
	v_cvt_pk_bf16_f32 v67, v68, v69
	v_mfma_f32_32x32x16_bf16 v[98:113], v[178:181], v[130:133], v[50:65]
	ds_read_b128 v[90:93], v248 offset:36896
	ds_read_b128 v[220:223], v248 offset:41504
	v_exp_f32_e32 v72, v72
	v_exp_f32_e32 v73, v73
	v_add_f32_e32 v246, v70, v246
	v_add_f32_e32 v246, v71, v246
	v_cvt_pk_bf16_f32 v68, v70, v71
	v_mfma_f32_32x32x16_bf16 v[114:129], v[166:169], v[134:137], v[114:129]
	ds_read_b128 v[94:97], v248 offset:36928
	ds_read_b128 v[224:227], v248 offset:41536
	v_exp_f32_e32 v74, v74
	v_exp_f32_e32 v75, v75
	v_add_f32_e32 v246, v72, v246
	v_add_f32_e32 v246, v73, v246
	v_cvt_pk_bf16_f32 v69, v72, v73
	v_mfma_f32_32x32x16_bf16 v[98:113], v[182:185], v[134:137], v[98:113]
	ds_read_b128 v[212:215], v248 offset:36960
	ds_read_b128 v[242:245], v248 offset:41568
	v_exp_f32_e32 v76, v76
	v_exp_f32_e32 v77, v77
	v_add_f32_e32 v246, v74, v246
	v_add_f32_e32 v246, v75, v246
	v_cvt_pk_bf16_f32 v70, v74, v75
	v_mfma_f32_32x32x16_bf16 v[114:129], v[170:173], v[138:141], v[114:129]
	v_exp_f32_e32 v78, v78
	v_exp_f32_e32 v79, v79
	v_add_f32_e32 v246, v76, v246
	v_add_f32_e32 v246, v77, v246
	v_cvt_pk_bf16_f32 v71, v76, v77
	v_mfma_f32_32x32x16_bf16 v[98:113], v[186:189], v[138:141], v[98:113]
	v_exp_f32_e32 v80, v80
	v_exp_f32_e32 v81, v81
	v_add_f32_e32 v246, v78, v246
	v_add_f32_e32 v246, v79, v246
	v_cvt_pk_bf16_f32 v72, v78, v79
	v_mfma_f32_32x32x16_bf16 v[114:129], v[174:177], v[142:145], v[114:129]
	s_cmp_ge_u32 s24, s16
	s_cbranch_scc1 .Lattn_fx_skipw1
	s_waitcnt vmcnt(2)
	ds_write_b128 v192, v[146:149] offset:18432
	ds_write_b128 v204, v[150:153] offset:27648
.Lattn_fx_skipw1:
	v_exp_f32_e32 v34, v34
	v_exp_f32_e32 v35, v35
	v_add_f32_e32 v246, v80, v246
	v_add_f32_e32 v246, v81, v246
	v_cvt_pk_bf16_f32 v73, v80, v81
	v_mfma_f32_32x32x16_bf16 v[98:113], v[82:85], v[142:145], v[98:113]
	v_exp_f32_e32 v36, v36
	v_exp_f32_e32 v37, v37
	v_add_f32_e32 v247, v34, v35
	v_cvt_pk_bf16_f32 v74, v34, v35
	s_waitcnt lgkmcnt(0)
	v_mfma_f32_32x32x16_bf16 v[18:33], v[86:89], v[66:69], v[18:33]
	s_barrier
	ds_read_b128 v[162:165], v193 offset:18432
	ds_read_b128 v[178:181], v193 offset:23040
	v_exp_f32_e32 v38, v38
	v_exp_f32_e32 v39, v39
	v_add_f32_e32 v247, v36, v247
	v_add_f32_e32 v247, v37, v247
	v_cvt_pk_bf16_f32 v75, v36, v37
	v_mfma_f32_32x32x16_bf16 v[2:17], v[216:219], v[66:69], v[2:17]
	ds_read_b128 v[166:169], v193 offset:18464
	ds_read_b128 v[182:185], v193 offset:23072
	v_exp_f32_e32 v40, v40
	v_exp_f32_e32 v41, v41
	v_add_f32_e32 v247, v38, v247
	v_add_f32_e32 v247, v39, v247
	v_cvt_pk_bf16_f32 v76, v38, v39
	v_mfma_f32_32x32x16_bf16 v[18:33], v[90:93], v[70:73], v[18:33]
	ds_read_b128 v[170:173], v193 offset:18496
	ds_read_b128 v[186:189], v193 offset:23104
	v_exp_f32_e32 v42, v42
	v_exp_f32_e32 v43, v43
	v_add_f32_e32 v247, v40, v247
	v_add_f32_e32 v247, v41, v247
	v_cvt_pk_bf16_f32 v77, v40, v41
	v_mfma_f32_32x32x16_bf16 v[2:17], v[220:223], v[70:73], v[2:17]
	ds_read_b128 v[174:177], v193 offset:18528
	ds_read_b128 v[82:85], v193 offset:23136
	v_exp_f32_e32 v44, v44
	v_exp_f32_e32 v45, v45
	v_add_f32_e32 v247, v42, v247
	v_add_f32_e32 v247, v43, v247
	v_cvt_pk_bf16_f32 v78, v42, v43
	v_mfma_f32_32x32x16_bf16 v[18:33], v[94:97], v[74:77], v[18:33]
	v_exp_f32_e32 v46, v46
	v_exp_f32_e32 v47, v47
	v_add_f32_e32 v247, v44, v247
	v_add_f32_e32 v247, v45, v247
	v_cvt_pk_bf16_f32 v79, v44, v45
	v_mfma_f32_32x32x16_bf16 v[2:17], v[224:227], v[74:77], v[2:17]
	v_exp_f32_e32 v48, v48
	v_exp_f32_e32 v49, v49
	v_add_f32_e32 v247, v46, v247
	v_add_f32_e32 v247, v47, v247
	v_cvt_pk_bf16_f32 v80, v46, v47
	v_cvt_pk_bf16_f32 v81, v48, v49
	v_add_f32_e32 v247, v48, v247
	v_add_f32_e32 v247, v49, v247
	v_mfma_f32_32x32x16_bf16 v[18:33], v[212:215], v[78:81], v[18:33]
	v_mfma_f32_32x32x16_bf16 v[2:17], v[242:245], v[78:81], v[2:17]
	v_add_f32_e32 v210, v210, v246
	v_add_f32_e32 v210, v210, v247
	s_min_i32 s24, s10, s58
	s_mul_i32 s44, s24, 0xa0000
	s_add_u32 s44, s3, s44
	s_addc_u32 s45, s12, 0
	s_lshl_b32 s46, s24, 7
	s_add_u32 s46, s15, s46
	s_addc_u32 s47, s23, 0
	global_load_dwordx4 v[146:149], v252, s[44:45] offset:1024
	global_load_dwordx4 v[150:153], v253, s[46:47]
	v_exp_f32_e32 v114, v114
	v_exp_f32_e32 v115, v115
	v_exp_f32_e32 v116, v116
	v_exp_f32_e32 v117, v117
	v_add_f32_e32 v246, v114, v115
	v_cvt_pk_bf16_f32 v114, v114, v115
	s_waitcnt lgkmcnt(0)
	v_mfma_f32_32x32x16_bf16 v[66:81], v[162:165], v[130:133], v[50:65]
	ds_read_b128 v[86:89], v248
	ds_read_b128 v[216:219], v248 offset:4608
	v_exp_f32_e32 v118, v118
	v_exp_f32_e32 v119, v119
	v_add_f32_e32 v246, v116, v246
	v_add_f32_e32 v246, v117, v246
	v_cvt_pk_bf16_f32 v115, v116, v117
	v_mfma_f32_32x32x16_bf16 v[34:49], v[178:181], v[130:133], v[50:65]
	ds_read_b128 v[90:93], v248 offset:32
	ds_read_b128 v[220:223], v248 offset:4640
	v_exp_f32_e32 v120, v120
	v_exp_f32_e32 v121, v121
	v_add_f32_e32 v246, v118, v246
	v_add_f32_e32 v246, v119, v246
	v_cvt_pk_bf16_f32 v116, v118, v119
	v_mfma_f32_32x32x16_bf16 v[66:81], v[166:169], v[134:137], v[66:81]
	ds_read_b128 v[94:97], v248 offset:64
	ds_read_b128 v[224:227], v248 offset:4672
	v_exp_f32_e32 v122, v122
	v_exp_f32_e32 v123, v123
	v_add_f32_e32 v246, v120, v246
	v_add_f32_e32 v246, v121, v246
	v_cvt_pk_bf16_f32 v117, v120, v121
	v_mfma_f32_32x32x16_bf16 v[34:49], v[182:185], v[134:137], v[34:49]
	ds_read_b128 v[212:215], v248 offset:96
	ds_read_b128 v[242:245], v248 offset:4704
	v_exp_f32_e32 v124, v124
	v_exp_f32_e32 v125, v125
	v_add_f32_e32 v246, v122, v246
	v_add_f32_e32 v246, v123, v246
	v_cvt_pk_bf16_f32 v118, v122, v123
	v_mfma_f32_32x32x16_bf16 v[66:81], v[170:173], v[138:141], v[66:81]
	v_exp_f32_e32 v126, v126
	v_exp_f32_e32 v127, v127
	v_add_f32_e32 v246, v124, v246
	v_add_f32_e32 v246, v125, v246
	v_cvt_pk_bf16_f32 v119, v124, v125
	v_mfma_f32_32x32x16_bf16 v[34:49], v[186:189], v[138:141], v[34:49]
	v_exp_f32_e32 v128, v128
	v_exp_f32_e32 v129, v129
	v_add_f32_e32 v246, v126, v246
	v_add_f32_e32 v246, v127, v246
	v_cvt_pk_bf16_f32 v120, v126, v127
	v_mfma_f32_32x32x16_bf16 v[66:81], v[174:177], v[142:145], v[66:81]
	s_cmp_ge_u32 s11, s16
	s_cbranch_scc1 .Lattn_fx_skipw2
	s_waitcnt vmcnt(2)
	ds_write_b128 v192, v[154:157] offset:55296
	ds_write_b128 v204, v[158:161] offset:64512
.Lattn_fx_skipw2:
	v_exp_f32_e32 v98, v98
	v_exp_f32_e32 v99, v99
	v_add_f32_e32 v246, v128, v246
	v_add_f32_e32 v246, v129, v246
	v_cvt_pk_bf16_f32 v121, v128, v129
	v_mfma_f32_32x32x16_bf16 v[34:49], v[82:85], v[142:145], v[34:49]
	v_exp_f32_e32 v100, v100
	v_exp_f32_e32 v101, v101
	v_add_f32_e32 v247, v98, v99
	v_cvt_pk_bf16_f32 v122, v98, v99
	s_waitcnt lgkmcnt(0)
	v_mfma_f32_32x32x16_bf16 v[18:33], v[86:89], v[114:117], v[18:33]
	s_barrier
	ds_read_b128 v[162:165], v193 offset:55296
	ds_read_b128 v[178:181], v193 offset:59904
	v_exp_f32_e32 v102, v102
	v_exp_f32_e32 v103, v103
	v_add_f32_e32 v247, v100, v247
	v_add_f32_e32 v247, v101, v247
	v_cvt_pk_bf16_f32 v123, v100, v101
	v_mfma_f32_32x32x16_bf16 v[2:17], v[216:219], v[114:117], v[2:17]
	ds_read_b128 v[166:169], v193 offset:55328
	ds_read_b128 v[182:185], v193 offset:59936
	v_exp_f32_e32 v104, v104
	v_exp_f32_e32 v105, v105
	v_add_f32_e32 v247, v102, v247
	v_add_f32_e32 v247, v103, v247
	v_cvt_pk_bf16_f32 v124, v102, v103
	v_mfma_f32_32x32x16_bf16 v[18:33], v[90:93], v[118:121], v[18:33]
	ds_read_b128 v[170:173], v193 offset:55360
	ds_read_b128 v[186:189], v193 offset:59968
	v_exp_f32_e32 v106, v106
	v_exp_f32_e32 v107, v107
	v_add_f32_e32 v247, v104, v247
	v_add_f32_e32 v247, v105, v247
	v_cvt_pk_bf16_f32 v125, v104, v105
	v_mfma_f32_32x32x16_bf16 v[2:17], v[220:223], v[118:121], v[2:17]
	ds_read_b128 v[174:177], v193 offset:55392
	ds_read_b128 v[82:85], v193 offset:60000
	v_exp_f32_e32 v108, v108
	v_exp_f32_e32 v109, v109
	v_add_f32_e32 v247, v106, v247
	v_add_f32_e32 v247, v107, v247
	v_cvt_pk_bf16_f32 v126, v106, v107
	v_mfma_f32_32x32x16_bf16 v[18:33], v[94:97], v[122:125], v[18:33]
	v_exp_f32_e32 v110, v110
	v_exp_f32_e32 v111, v111
	v_add_f32_e32 v247, v108, v247
	v_add_f32_e32 v247, v109, v247
	v_cvt_pk_bf16_f32 v127, v108, v109
	v_mfma_f32_32x32x16_bf16 v[2:17], v[224:227], v[122:125], v[2:17]
	v_exp_f32_e32 v112, v112
	v_exp_f32_e32 v113, v113
	v_add_f32_e32 v247, v110, v247
	v_add_f32_e32 v247, v111, v247
	v_cvt_pk_bf16_f32 v128, v110, v111
	v_cvt_pk_bf16_f32 v129, v112, v113
	v_add_f32_e32 v247, v112, v247
	v_add_f32_e32 v247, v113, v247
	v_mfma_f32_32x32x16_bf16 v[18:33], v[212:215], v[126:129], v[18:33]
	v_mfma_f32_32x32x16_bf16 v[2:17], v[242:245], v[126:129], v[2:17]
	v_add_f32_e32 v210, v210, v246
	v_add_f32_e32 v210, v210, v247
	s_add_i32 s10, s10, 2
	s_cmp_lt_u32 s11, s16
	s_cbranch_scc0 .Lattn_fx_exit0
	s_add_i32 s11, s10, -1
	s_min_i32 s1, s11, s58
	s_mul_i32 s44, s1, 0xa0000
	s_add_u32 s44, s3, s44
	s_addc_u32 s45, s12, 0
	s_lshl_b32 s46, s1, 7
	s_add_u32 s46, s15, s46
	s_addc_u32 s47, s23, 0
	s_add_i32 s24, s10, -2
	s_cmp_lt_u32 s24, s16
	s_cselect_b64 s[0:1], -1, 0
	global_load_dwordx4 v[154:157], v252, s[44:45] offset:1024
	global_load_dwordx4 v[158:161], v253, s[46:47]
	v_exp_f32_e32 v66, v66
	v_exp_f32_e32 v67, v67
	v_exp_f32_e32 v68, v68
	v_exp_f32_e32 v69, v69
	v_add_f32_e32 v246, v66, v67
	v_cvt_pk_bf16_f32 v66, v66, v67
	s_waitcnt lgkmcnt(0)
	v_mfma_f32_32x32x16_bf16 v[114:129], v[162:165], v[130:133], v[50:65]
	ds_read_b128 v[86:89], v248 offset:18432
	ds_read_b128 v[216:219], v248 offset:23040
	v_exp_f32_e32 v70, v70
	v_exp_f32_e32 v71, v71
	v_add_f32_e32 v246, v68, v246
	v_add_f32_e32 v246, v69, v246
	v_cvt_pk_bf16_f32 v67, v68, v69
	v_mfma_f32_32x32x16_bf16 v[98:113], v[178:181], v[130:133], v[50:65]
	ds_read_b128 v[90:93], v248 offset:18464
	ds_read_b128 v[220:223], v248 offset:23072
	v_exp_f32_e32 v72, v72
	v_exp_f32_e32 v73, v73
	v_add_f32_e32 v246, v70, v246
	v_add_f32_e32 v246, v71, v246
	v_cvt_pk_bf16_f32 v68, v70, v71
	v_mfma_f32_32x32x16_bf16 v[114:129], v[166:169], v[134:137], v[114:129]
	ds_read_b128 v[94:97], v248 offset:18496
	ds_read_b128 v[224:227], v248 offset:23104
	v_exp_f32_e32 v74, v74
	v_exp_f32_e32 v75, v75
	v_add_f32_e32 v246, v72, v246
	v_add_f32_e32 v246, v73, v246
	v_cvt_pk_bf16_f32 v69, v72, v73
	v_mfma_f32_32x32x16_bf16 v[98:113], v[182:185], v[134:137], v[98:113]
	ds_read_b128 v[212:215], v248 offset:18528
	ds_read_b128 v[242:245], v248 offset:23136
	v_exp_f32_e32 v76, v76
	v_exp_f32_e32 v77, v77
	v_add_f32_e32 v246, v74, v246
	v_add_f32_e32 v246, v75, v246
	v_cvt_pk_bf16_f32 v70, v74, v75
	v_mfma_f32_32x32x16_bf16 v[114:129], v[170:173], v[138:141], v[114:129]
	v_exp_f32_e32 v78, v78
	v_exp_f32_e32 v79, v79
	v_add_f32_e32 v246, v76, v246
	v_add_f32_e32 v246, v77, v246
	v_cvt_pk_bf16_f32 v71, v76, v77
	v_mfma_f32_32x32x16_bf16 v[98:113], v[186:189], v[138:141], v[98:113]
	v_exp_f32_e32 v80, v80
	v_exp_f32_e32 v81, v81
	v_add_f32_e32 v246, v78, v246
	v_add_f32_e32 v246, v79, v246
	v_cvt_pk_bf16_f32 v72, v78, v79
	v_mfma_f32_32x32x16_bf16 v[114:129], v[174:177], v[142:145], v[114:129]
	s_cmp_ge_u32 s24, s16
	s_cbranch_scc1 .Lattn_fx_skipw3
	s_waitcnt vmcnt(2)
	ds_write_b128 v192, v[146:149] offset:36864
	ds_write_b128 v204, v[150:153] offset:46080
.Lattn_fx_skipw3:
	v_exp_f32_e32 v34, v34
	v_exp_f32_e32 v35, v35
	v_add_f32_e32 v246, v80, v246
	v_add_f32_e32 v246, v81, v246
	v_cvt_pk_bf16_f32 v73, v80, v81
	v_mfma_f32_32x32x16_bf16 v[98:113], v[82:85], v[142:145], v[98:113]
	v_exp_f32_e32 v36, v36
	v_exp_f32_e32 v37, v37
	v_add_f32_e32 v247, v34, v35
	v_cvt_pk_bf16_f32 v74, v34, v35
	s_waitcnt lgkmcnt(0)
	v_mfma_f32_32x32x16_bf16 v[18:33], v[86:89], v[66:69], v[18:33]
	s_barrier
	ds_read_b128 v[162:165], v193 offset:36864
	ds_read_b128 v[178:181], v193 offset:41472
	v_exp_f32_e32 v38, v38
	v_exp_f32_e32 v39, v39
	v_add_f32_e32 v247, v36, v247
	v_add_f32_e32 v247, v37, v247
	v_cvt_pk_bf16_f32 v75, v36, v37
	v_mfma_f32_32x32x16_bf16 v[2:17], v[216:219], v[66:69], v[2:17]
	ds_read_b128 v[166:169], v193 offset:36896
	ds_read_b128 v[182:185], v193 offset:41504
	v_exp_f32_e32 v40, v40
	v_exp_f32_e32 v41, v41
	v_add_f32_e32 v247, v38, v247
	v_add_f32_e32 v247, v39, v247
	v_cvt_pk_bf16_f32 v76, v38, v39
	v_mfma_f32_32x32x16_bf16 v[18:33], v[90:93], v[70:73], v[18:33]
	ds_read_b128 v[170:173], v193 offset:36928
	ds_read_b128 v[186:189], v193 offset:41536
	v_exp_f32_e32 v42, v42
	v_exp_f32_e32 v43, v43
	v_add_f32_e32 v247, v40, v247
	v_add_f32_e32 v247, v41, v247
	v_cvt_pk_bf16_f32 v77, v40, v41
	v_mfma_f32_32x32x16_bf16 v[2:17], v[220:223], v[70:73], v[2:17]
	ds_read_b128 v[174:177], v193 offset:36960
	ds_read_b128 v[82:85], v193 offset:41568
	v_exp_f32_e32 v44, v44
	v_exp_f32_e32 v45, v45
	v_add_f32_e32 v247, v42, v247
	v_add_f32_e32 v247, v43, v247
	v_cvt_pk_bf16_f32 v78, v42, v43
	v_mfma_f32_32x32x16_bf16 v[18:33], v[94:97], v[74:77], v[18:33]
	v_exp_f32_e32 v46, v46
	v_exp_f32_e32 v47, v47
	v_add_f32_e32 v247, v44, v247
	v_add_f32_e32 v247, v45, v247
	v_cvt_pk_bf16_f32 v79, v44, v45
	v_mfma_f32_32x32x16_bf16 v[2:17], v[224:227], v[74:77], v[2:17]
	v_exp_f32_e32 v48, v48
	v_exp_f32_e32 v49, v49
	v_add_f32_e32 v247, v46, v247
	v_add_f32_e32 v247, v47, v247
	v_cvt_pk_bf16_f32 v80, v46, v47
	v_cvt_pk_bf16_f32 v81, v48, v49
	v_add_f32_e32 v247, v48, v247
	v_add_f32_e32 v247, v49, v247
	v_mfma_f32_32x32x16_bf16 v[18:33], v[212:215], v[78:81], v[18:33]
	v_mfma_f32_32x32x16_bf16 v[2:17], v[242:245], v[78:81], v[2:17]
	v_add_f32_e32 v210, v210, v246
	v_add_f32_e32 v210, v210, v247
	s_min_i32 s24, s10, s58
	s_mul_i32 s44, s24, 0xa0000
	s_add_u32 s44, s3, s44
	s_addc_u32 s45, s12, 0
	s_lshl_b32 s46, s24, 7
	s_add_u32 s46, s15, s46
	s_addc_u32 s47, s23, 0
	global_load_dwordx4 v[146:149], v252, s[44:45] offset:1024
	global_load_dwordx4 v[150:153], v253, s[46:47]
	v_exp_f32_e32 v114, v114
	v_exp_f32_e32 v115, v115
	v_exp_f32_e32 v116, v116
	v_exp_f32_e32 v117, v117
	v_add_f32_e32 v246, v114, v115
	v_cvt_pk_bf16_f32 v114, v114, v115
	s_waitcnt lgkmcnt(0)
	v_mfma_f32_32x32x16_bf16 v[66:81], v[162:165], v[130:133], v[50:65]
	ds_read_b128 v[86:89], v248 offset:55296
	ds_read_b128 v[216:219], v248 offset:59904
	v_exp_f32_e32 v118, v118
	v_exp_f32_e32 v119, v119
	v_add_f32_e32 v246, v116, v246
	v_add_f32_e32 v246, v117, v246
	v_cvt_pk_bf16_f32 v115, v116, v117
	v_mfma_f32_32x32x16_bf16 v[34:49], v[178:181], v[130:133], v[50:65]
	ds_read_b128 v[90:93], v248 offset:55328
	ds_read_b128 v[220:223], v248 offset:59936
	v_exp_f32_e32 v120, v120
	v_exp_f32_e32 v121, v121
	v_add_f32_e32 v246, v118, v246
	v_add_f32_e32 v246, v119, v246
	v_cvt_pk_bf16_f32 v116, v118, v119
	v_mfma_f32_32x32x16_bf16 v[66:81], v[166:169], v[134:137], v[66:81]
	ds_read_b128 v[94:97], v248 offset:55360
	ds_read_b128 v[224:227], v248 offset:59968
	v_exp_f32_e32 v122, v122
	v_exp_f32_e32 v123, v123
	v_add_f32_e32 v246, v120, v246
	v_add_f32_e32 v246, v121, v246
	v_cvt_pk_bf16_f32 v117, v120, v121
	v_mfma_f32_32x32x16_bf16 v[34:49], v[182:185], v[134:137], v[34:49]
	ds_read_b128 v[212:215], v248 offset:55392
	ds_read_b128 v[242:245], v248 offset:60000
	v_exp_f32_e32 v124, v124
	v_exp_f32_e32 v125, v125
	v_add_f32_e32 v246, v122, v246
	v_add_f32_e32 v246, v123, v246
	v_cvt_pk_bf16_f32 v118, v122, v123
	v_mfma_f32_32x32x16_bf16 v[66:81], v[170:173], v[138:141], v[66:81]
	v_exp_f32_e32 v126, v126
	v_exp_f32_e32 v127, v127
	v_add_f32_e32 v246, v124, v246
	v_add_f32_e32 v246, v125, v246
	v_cvt_pk_bf16_f32 v119, v124, v125
	v_mfma_f32_32x32x16_bf16 v[34:49], v[186:189], v[138:141], v[34:49]
	v_exp_f32_e32 v128, v128
	v_exp_f32_e32 v129, v129
	v_add_f32_e32 v246, v126, v246
	v_add_f32_e32 v246, v127, v246
	v_cvt_pk_bf16_f32 v120, v126, v127
	v_mfma_f32_32x32x16_bf16 v[66:81], v[174:177], v[142:145], v[66:81]
	s_cmp_ge_u32 s11, s16
	s_cbranch_scc1 .Lattn_fx_skipw4
	s_waitcnt vmcnt(2)
	ds_write_b128 v192, v[154:157]
	ds_write_b128 v204, v[158:161] offset:9216
; template <int HD, int MODE> ...
;     ...
;     int t = t0;
;     for (; t + 1 < t1; t += 2) { ATT_STEP(sa0, sa1, sb0, sb1, t, kstB, vstB, kstA, vstA); ATT_STEP(sb0, sb1, sa0, sa1, t + 1, kstA, vstA, kstB, vstB); }
.Lattn_fx_skipw4:
	v_exp_f32_e32 v98, v98
	v_exp_f32_e32 v99, v99
	v_add_f32_e32 v246, v128, v246
	v_add_f32_e32 v246, v129, v246
	v_cvt_pk_bf16_f32 v121, v128, v129
	v_mfma_f32_32x32x16_bf16 v[34:49], v[82:85], v[142:145], v[34:49]
	v_exp_f32_e32 v100, v100
	v_exp_f32_e32 v101, v101
	v_add_f32_e32 v247, v98, v99
	v_cvt_pk_bf16_f32 v122, v98, v99
	s_waitcnt lgkmcnt(0)
	v_mfma_f32_32x32x16_bf16 v[18:33], v[86:89], v[114:117], v[18:33]
	s_barrier
	ds_read_b128 v[162:165], v193
	ds_read_b128 v[178:181], v193 offset:4608
	v_exp_f32_e32 v102, v102
	v_exp_f32_e32 v103, v103
	v_add_f32_e32 v247, v100, v247
	v_add_f32_e32 v247, v101, v247
	v_cvt_pk_bf16_f32 v123, v100, v101
	v_mfma_f32_32x32x16_bf16 v[2:17], v[216:219], v[114:117], v[2:17]
	ds_read_b128 v[166:169], v193 offset:32
	ds_read_b128 v[182:185], v193 offset:4640
	v_exp_f32_e32 v104, v104
	v_exp_f32_e32 v105, v105
	v_add_f32_e32 v247, v102, v247
	v_add_f32_e32 v247, v103, v247
	v_cvt_pk_bf16_f32 v124, v102, v103
	v_mfma_f32_32x32x16_bf16 v[18:33], v[90:93], v[118:121], v[18:33]
	ds_read_b128 v[170:173], v193 offset:64
	ds_read_b128 v[186:189], v193 offset:4672
	v_exp_f32_e32 v106, v106
	v_exp_f32_e32 v107, v107
	v_add_f32_e32 v247, v104, v247
	v_add_f32_e32 v247, v105, v247
	v_cvt_pk_bf16_f32 v125, v104, v105
	v_mfma_f32_32x32x16_bf16 v[2:17], v[220:223], v[118:121], v[2:17]
	ds_read_b128 v[174:177], v193 offset:96
	ds_read_b128 v[82:85], v193 offset:4704
	v_exp_f32_e32 v108, v108
	v_exp_f32_e32 v109, v109
	v_add_f32_e32 v247, v106, v247
	v_add_f32_e32 v247, v107, v247
	v_cvt_pk_bf16_f32 v126, v106, v107
	v_mfma_f32_32x32x16_bf16 v[18:33], v[94:97], v[122:125], v[18:33]
	v_exp_f32_e32 v110, v110
	v_exp_f32_e32 v111, v111
	v_add_f32_e32 v247, v108, v247
	v_add_f32_e32 v247, v109, v247
	v_cvt_pk_bf16_f32 v127, v108, v109
	v_mfma_f32_32x32x16_bf16 v[2:17], v[224:227], v[122:125], v[2:17]
	v_exp_f32_e32 v112, v112
	v_exp_f32_e32 v113, v113
	v_add_f32_e32 v247, v110, v247
	v_add_f32_e32 v247, v111, v247
	v_cvt_pk_bf16_f32 v128, v110, v111
	v_cvt_pk_bf16_f32 v129, v112, v113
	v_add_f32_e32 v247, v112, v247
	v_add_f32_e32 v247, v113, v247
	v_mfma_f32_32x32x16_bf16 v[18:33], v[212:215], v[126:129], v[18:33]
	v_mfma_f32_32x32x16_bf16 v[2:17], v[242:245], v[126:129], v[2:17]
	v_add_f32_e32 v210, v210, v246
	v_add_f32_e32 v210, v210, v247
	s_add_i32 s10, s10, 2
	s_cmp_lt_u32 s11, s16
	s_cbranch_scc0 .Lattn_fx_exit1
	s_branch .Lattn_fx_top
